# grid barrier: the first workgroup to arrive on each XCD starts an early non-blocking buffer_wbl2 sc1, so the leader's release writeback has less dirty L2 left
# baseline (speedup 1.0000x reference)
.LBB0_131:
	s_lshl_b32 s0, s36, 8
	s_add_u32 s0, s34, s0
	s_addc_u32 s1, s35, 0
	v_mov_b32_e32 v1, s0
	v_add_co_u32_e32 v4, vcc, 0x601000, v1
	v_mov_b32_e32 v1, s1
	s_nop 0
	v_addc_co_u32_e32 v5, vcc, 0, v1, vcc
	v_mov_b32_e32 v1, 1
	flat_atomic_add v1, v[4:5], v1 offset:1024 sc0
	v_cvt_f32_u32_e32 v3, v2
	v_sub_u32_e32 v4, 0, v2
	s_add_u32 s23, s0, 0x600000
	s_addc_u32 s22, s1, 0
	v_rcp_iflag_f32_e32 v3, v3
	s_nop 0
	v_mul_f32_e32 v3, 0x4f7ffffe, v3
	v_cvt_u32_f32_e32 v3, v3
	v_mul_lo_u32 v4, v4, v3
	v_mul_hi_u32 v4, v3, v4
	v_add_u32_e32 v3, v3, v4
	s_waitcnt vmcnt(0) lgkmcnt(0)
	v_mul_hi_u32 v3, v1, v3
	v_mul_lo_u32 v5, v3, v2
	v_add_u32_e32 v4, 1, v1
	v_sub_u32_e32 v1, v1, v5
	v_add_u32_e32 v6, 1, v3
	v_cmp_ge_u32_e32 vcc, v1, v2
	v_sub_u32_e32 v5, v1, v2
	s_nop 0
	v_cndmask_b32_e32 v3, v3, v6, vcc
	v_cndmask_b32_e32 v1, v1, v5, vcc
	v_add_u32_e32 v5, 1, v3
	v_cmp_ge_u32_e32 vcc, v1, v2
	s_nop 1
	v_cndmask_b32_e32 v1, v3, v5, vcc
	v_mul_lo_u32 v5, v2, v1
	v_add_u32_e32 v5, 1, v5
	v_mad_u64_u32 v[2:3], s[0:1], v2, v1, v[2:3]
	v_cmp_ne_u32_e32 vcc, v4, v2
	s_and_saveexec_b64 s[0:1], vcc
	s_xor_b64 s[0:1], exec, s[0:1]
	s_cbranch_execz .LBB0_144
	v_cmp_ne_u32_e32 vcc, v4, v5
	s_nop 3
	s_cbranch_vccnz .Lgs_nf_0
	buffer_wbl2 sc1
.Lgs_nf_0:
	v_mov_b32_e32 v0, s23
	v_add_co_u32_e32 v2, vcc, 0x2000, v0
	v_mov_b32_e32 v0, s22
	s_nop 0
	v_addc_co_u32_e32 v3, vcc, 0, v0, vcc
	flat_load_dword v0, v[2:3] offset:1024 sc1
	s_add_u32 s6, s23, 0x2400
	s_addc_u32 s7, s22, 0
	s_waitcnt vmcnt(0) lgkmcnt(0)
	v_cmp_eq_u32_e32 vcc, v0, v1
	s_and_saveexec_b64 s[2:3], vcc
	s_cbranch_execz .LBB0_143
	s_add_u32 s4, s34, 0x600200
	s_addc_u32 s5, s35, 0
	s_mov_b32 s24, 1
	s_mov_b64 s[8:9], 0
	s_branch .LBB0_135

.LBB0_276:
	s_lshl_b32 s0, s63, 8
	s_add_u32 s0, s44, s0
	s_addc_u32 s1, s62, 0
	v_mov_b32_e32 v1, s0
	v_add_co_u32_e32 v4, vcc, 0x601000, v1
	v_mov_b32_e32 v1, s1
	s_nop 0
	v_addc_co_u32_e32 v5, vcc, 0, v1, vcc
	flat_atomic_add v3, v[4:5], v219 offset:1024 sc0
	v_cvt_f32_u32_e32 v1, v2
	v_sub_u32_e32 v4, 0, v2
	s_add_u32 s23, s0, 0x600000
	s_addc_u32 s22, s1, 0
	v_rcp_iflag_f32_e32 v1, v1
	s_nop 0
	v_mul_f32_e32 v1, 0x4f7ffffe, v1
	v_cvt_u32_f32_e32 v1, v1
	v_mul_lo_u32 v4, v4, v1
	v_mul_hi_u32 v4, v1, v4
	v_add_u32_e32 v1, v1, v4
	s_waitcnt vmcnt(0) lgkmcnt(0)
	v_mul_hi_u32 v1, v3, v1
	v_mul_lo_u32 v4, v1, v2
	v_sub_u32_e32 v4, v3, v4
	v_cmp_ge_u32_e32 vcc, v4, v2
	v_add_u32_e32 v5, 1, v1
	s_nop 0
	v_cndmask_b32_e32 v1, v1, v5, vcc
	v_sub_u32_e32 v5, v4, v2
	v_cndmask_b32_e32 v4, v4, v5, vcc
	v_cmp_ge_u32_e32 vcc, v4, v2
	v_add_u32_e32 v4, 1, v1
	s_nop 0
	v_cndmask_b32_e32 v1, v1, v4, vcc
	v_add_u32_e32 v4, 1, v3
	v_mul_lo_u32 v5, v2, v1
	v_add_u32_e32 v5, 1, v5
	v_mad_u64_u32 v[2:3], s[0:1], v2, v1, v[2:3]
	v_cmp_ne_u32_e32 vcc, v4, v2
	s_and_saveexec_b64 s[0:1], vcc
	s_xor_b64 s[0:1], exec, s[0:1]
	s_cbranch_execz .LBB0_289
	v_cmp_ne_u32_e32 vcc, v4, v5
	s_nop 3
	s_cbranch_vccnz .Lgs_nf_2
	buffer_wbl2 sc1
.Lgs_nf_2:
	v_mov_b32_e32 v0, s23
	v_add_co_u32_e32 v2, vcc, 0x2000, v0
	v_mov_b32_e32 v0, s22
	s_nop 0
	v_addc_co_u32_e32 v3, vcc, 0, v0, vcc
	flat_load_dword v0, v[2:3] offset:1024 sc1
	s_add_u32 s4, s23, 0x2400
	s_addc_u32 s5, s22, 0
	s_waitcnt vmcnt(0) lgkmcnt(0)
	v_cmp_eq_u32_e32 vcc, v0, v1
	s_and_saveexec_b64 s[2:3], vcc
	s_cbranch_execz .LBB0_288
	s_add_u32 s6, s44, 0x600200
	s_addc_u32 s7, s62, 0
	s_mov_b32 s24, 1
	s_mov_b64 s[8:9], 0
	s_branch .LBB0_280

.LBB0_375:
	s_lshl_b32 s0, s62, 8
	s_add_u32 s0, s43, s0
	s_addc_u32 s1, s44, 0
	v_mov_b32_e32 v1, s0
	v_add_co_u32_e32 v4, vcc, 0x601000, v1
	v_mov_b32_e32 v1, s1
	s_nop 0
	v_addc_co_u32_e32 v5, vcc, 0, v1, vcc
	flat_atomic_add v3, v[4:5], v219 offset:1024 sc0
	v_cvt_f32_u32_e32 v1, v2
	v_sub_u32_e32 v4, 0, v2
	s_add_u32 s23, s0, 0x600000
	s_addc_u32 s22, s1, 0
	v_rcp_iflag_f32_e32 v1, v1
	s_nop 0
	v_mul_f32_e32 v1, 0x4f7ffffe, v1
	v_cvt_u32_f32_e32 v1, v1
	v_mul_lo_u32 v4, v4, v1
	v_mul_hi_u32 v4, v1, v4
	v_add_u32_e32 v1, v1, v4
	s_waitcnt vmcnt(0) lgkmcnt(0)
	v_mul_hi_u32 v1, v3, v1
	v_mul_lo_u32 v4, v1, v2
	v_sub_u32_e32 v4, v3, v4
	v_cmp_ge_u32_e32 vcc, v4, v2
	v_add_u32_e32 v5, 1, v1
	s_nop 0
	v_cndmask_b32_e32 v1, v1, v5, vcc
	v_sub_u32_e32 v5, v4, v2
	v_cndmask_b32_e32 v4, v4, v5, vcc
	v_cmp_ge_u32_e32 vcc, v4, v2
	v_add_u32_e32 v4, 1, v1
	s_nop 0
	v_cndmask_b32_e32 v1, v1, v4, vcc
	v_add_u32_e32 v4, 1, v3
	v_mul_lo_u32 v5, v2, v1
	v_add_u32_e32 v5, 1, v5
	v_mad_u64_u32 v[2:3], s[0:1], v2, v1, v[2:3]
	v_cmp_ne_u32_e32 vcc, v4, v2
	s_and_saveexec_b64 s[0:1], vcc
	s_xor_b64 s[0:1], exec, s[0:1]
	s_cbranch_execz .LBB0_388
	v_cmp_ne_u32_e32 vcc, v4, v5
	s_nop 3
	s_cbranch_vccnz .Lgs_nf_3
	buffer_wbl2 sc1
.Lgs_nf_3:
	v_mov_b32_e32 v0, s23
	v_add_co_u32_e32 v2, vcc, 0x2000, v0
	v_mov_b32_e32 v0, s22
	s_nop 0
	v_addc_co_u32_e32 v3, vcc, 0, v0, vcc
	flat_load_dword v0, v[2:3] offset:1024 sc1
	s_add_u32 s4, s23, 0x2400
	s_addc_u32 s5, s22, 0
	s_waitcnt vmcnt(0) lgkmcnt(0)
	v_cmp_eq_u32_e32 vcc, v0, v1
	s_and_saveexec_b64 s[2:3], vcc
	s_cbranch_execz .LBB0_387
	s_add_u32 s6, s43, 0x600200
	s_addc_u32 s7, s44, 0
	s_mov_b32 s24, 1
	s_mov_b64 s[8:9], 0
	s_branch .LBB0_379

.LBB0_662:
	s_lshl_b32 s0, s43, 8
	s_add_u32 s0, s37, s0
	s_addc_u32 s1, s42, 0
	v_mov_b32_e32 v1, s0
	v_add_co_u32_e32 v4, vcc, 0x601000, v1
	v_mov_b32_e32 v1, s1
	s_nop 0
	v_addc_co_u32_e32 v5, vcc, 0, v1, vcc
	flat_atomic_add v3, v[4:5], v219 offset:1024 sc0
	v_cvt_f32_u32_e32 v1, v2
	v_sub_u32_e32 v4, 0, v2
	s_add_u32 s23, s0, 0x600000
	s_addc_u32 s22, s1, 0
	v_rcp_iflag_f32_e32 v1, v1
	s_nop 0
	v_mul_f32_e32 v1, 0x4f7ffffe, v1
	v_cvt_u32_f32_e32 v1, v1
	v_mul_lo_u32 v4, v4, v1
	v_mul_hi_u32 v4, v1, v4
	v_add_u32_e32 v1, v1, v4
	s_waitcnt vmcnt(0) lgkmcnt(0)
	v_mul_hi_u32 v1, v3, v1
	v_mul_lo_u32 v4, v1, v2
	v_sub_u32_e32 v4, v3, v4
	v_cmp_ge_u32_e32 vcc, v4, v2
	v_add_u32_e32 v5, 1, v1
	s_nop 0
	v_cndmask_b32_e32 v1, v1, v5, vcc
	v_sub_u32_e32 v5, v4, v2
	v_cndmask_b32_e32 v4, v4, v5, vcc
	v_cmp_ge_u32_e32 vcc, v4, v2
	v_add_u32_e32 v4, 1, v1
	s_nop 0
	v_cndmask_b32_e32 v1, v1, v4, vcc
	v_add_u32_e32 v4, 1, v3
	v_mul_lo_u32 v5, v2, v1
	v_add_u32_e32 v5, 1, v5
	v_mad_u64_u32 v[2:3], s[0:1], v2, v1, v[2:3]
	v_cmp_ne_u32_e32 vcc, v4, v2
	s_and_saveexec_b64 s[0:1], vcc
	s_xor_b64 s[0:1], exec, s[0:1]
	s_cbranch_execz .LBB0_675
	v_cmp_ne_u32_e32 vcc, v4, v5
	s_nop 3
	s_cbranch_vccnz .Lgs_nf_7
	buffer_wbl2 sc1
.Lgs_nf_7:
	v_mov_b32_e32 v0, s23
	v_add_co_u32_e32 v2, vcc, 0x2000, v0
	v_mov_b32_e32 v0, s22
	s_nop 0
	v_addc_co_u32_e32 v3, vcc, 0, v0, vcc
	flat_load_dword v0, v[2:3] offset:1024 sc1
	s_add_u32 s4, s23, 0x2400
	s_addc_u32 s5, s22, 0
	s_waitcnt vmcnt(0) lgkmcnt(0)
	v_cmp_eq_u32_e32 vcc, v0, v1
	s_and_saveexec_b64 s[2:3], vcc
	s_cbranch_execz .LBB0_674
	s_add_u32 s6, s37, 0x600200
	s_addc_u32 s7, s42, 0
	s_mov_b32 s24, 1
	s_mov_b64 s[8:9], 0
	s_branch .LBB0_666

.LBB0_1305:
	s_lshl_b32 s0, s62, 8
	s_add_u32 s0, s37, s0
	s_addc_u32 s1, s44, 0
	v_mov_b32_e32 v1, s0
	v_add_co_u32_e32 v4, vcc, 0x601000, v1
	v_mov_b32_e32 v1, s1
	s_nop 0
	v_addc_co_u32_e32 v5, vcc, 0, v1, vcc
	flat_atomic_add v3, v[4:5], v219 offset:1024 sc0
	v_cvt_f32_u32_e32 v1, v2
	v_sub_u32_e32 v4, 0, v2
	s_add_u32 s23, s0, 0x600000
	s_addc_u32 s22, s1, 0
	v_rcp_iflag_f32_e32 v1, v1
	s_nop 0
	v_mul_f32_e32 v1, 0x4f7ffffe, v1
	v_cvt_u32_f32_e32 v1, v1
	v_mul_lo_u32 v4, v4, v1
	v_mul_hi_u32 v4, v1, v4
	v_add_u32_e32 v1, v1, v4
	s_waitcnt vmcnt(0) lgkmcnt(0)
	v_mul_hi_u32 v1, v3, v1
	v_mul_lo_u32 v4, v1, v2
	v_sub_u32_e32 v4, v3, v4
	v_cmp_ge_u32_e32 vcc, v4, v2
	v_add_u32_e32 v5, 1, v1
	s_nop 0
	v_cndmask_b32_e32 v1, v1, v5, vcc
	v_sub_u32_e32 v5, v4, v2
	v_cndmask_b32_e32 v4, v4, v5, vcc
	v_cmp_ge_u32_e32 vcc, v4, v2
	v_add_u32_e32 v4, 1, v1
	s_nop 0
	v_cndmask_b32_e32 v1, v1, v4, vcc
	v_add_u32_e32 v4, 1, v3
	v_mul_lo_u32 v5, v2, v1
	v_add_u32_e32 v5, 1, v5
	v_mad_u64_u32 v[2:3], s[0:1], v2, v1, v[2:3]
	v_cmp_ne_u32_e32 vcc, v4, v2
	s_and_saveexec_b64 s[0:1], vcc
	s_xor_b64 s[0:1], exec, s[0:1]
	s_cbranch_execz .LBB0_1318
	v_cmp_ne_u32_e32 vcc, v4, v5
	s_nop 3
	s_cbranch_vccnz .Lgs_nf_9
	buffer_wbl2 sc1
.Lgs_nf_9:
	v_mov_b32_e32 v0, s23
	v_add_co_u32_e32 v2, vcc, 0x2000, v0
	v_mov_b32_e32 v0, s22
	s_nop 0
	v_addc_co_u32_e32 v3, vcc, 0, v0, vcc
	flat_load_dword v0, v[2:3] offset:1024 sc1
	s_add_u32 s4, s23, 0x2400
	s_addc_u32 s5, s22, 0
	s_waitcnt vmcnt(0) lgkmcnt(0)
	v_cmp_eq_u32_e32 vcc, v0, v1
	s_and_saveexec_b64 s[2:3], vcc
	s_cbranch_execz .LBB0_1317
	s_add_u32 s6, s37, 0x600200
	s_addc_u32 s7, s44, 0
	s_mov_b32 s24, 1
	s_mov_b64 s[8:9], 0
	s_branch .LBB0_1309
